# residual epilogue: gate / gain / scale / shift vectors requested together with the xb tile before the first wait (free K-loop registers), norm loop copies instead of loading
# baseline (speedup 1.0000x reference)
.LBB0_782:
	s_mul_i32 s4, s2, 0x1b000
	s_add_u32 s4, s18, s4
	s_mul_hi_i32 s5, s2, 0x1b000
	s_addc_u32 s5, s19, s5
	s_add_u32 s72, s4, 0x100000
	s_addc_u32 s73, s5, 0
	s_lshl_b32 s4, s71, 2
	s_add_u32 s12, s72, s4
	s_addc_u32 s13, s73, 0
	s_ashr_i32 s4, s6, 5
	s_mul_hi_i32 s5, s4, 0x2400
	s_mulk_i32 s4, 0x2400
	s_lshl_b64 s[4:5], s[4:5], 2
	s_add_u32 s12, s12, s4
	s_addc_u32 s13, s13, s5
	v_lshl_add_u64 v[154:155], v[148:149], 2, s[12:13]
	global_load_dwordx4 v[134:137], v[154:155], off offset:16
	global_load_dwordx4 v[142:145], v[154:155], off
	global_load_dwordx4 v[168:171], v[154:155], off offset:528
	global_load_dwordx4 v[172:175], v[154:155], off offset:512
	v_lshlrev_b32_e32 v216, 2, v148
	global_load_dwordx4 v[176:179], v216, s[36:37] offset:16
	global_load_dwordx4 v[180:183], v216, s[36:37]
	global_load_dwordx4 v[184:187], v216, s[36:37] offset:528
	global_load_dwordx4 v[188:191], v216, s[36:37] offset:512
	s_and_b64 vcc, exec, s[30:31]
	s_cbranch_vccz .Lcab_nomods
	v_readlane_b32 s12, v255, 5
	v_readlane_b32 s13, v255, 4
	s_add_u32 s98, s72, s12
	s_addc_u32 s99, s73, 0
	s_lshl_b32 s13, s13, 2
	s_add_u32 s98, s98, s13
	s_addc_u32 s99, s99, 0
	s_add_u32 s98, s98, s4
	s_addc_u32 s99, s99, s5
	s_add_u32 s100, s98, 0x1000
	s_addc_u32 s101, s99, 0
	global_load_dwordx4 v[192:195], v216, s[100:101] offset:16
	global_load_dwordx4 v[196:199], v216, s[100:101]
	global_load_dwordx4 v[200:203], v216, s[100:101] offset:528
	global_load_dwordx4 v[204:207], v216, s[100:101] offset:512
	global_load_dwordx4 v[208:211], v216, s[98:99]
	global_load_dwordx4 v[212:215], v216, s[98:99] offset:16
	global_load_dwordx4 v[220:223], v216, s[98:99] offset:512
	global_load_dwordx4 v[224:227], v216, s[98:99] offset:528
.Lcab_nomods:
	v_and_b32_e32 v0, 63, v163
	v_lshlrev_b32_e32 v130, 4, v0
	s_mov_b64 s[12:13], -1
	s_and_b64 vcc, exec, s[38:39]
	v_add_u32_e32 v165, s7, v130
	s_cbranch_vccz .LBB0_784
	s_waitcnt vmcnt(0)
	ds_read_b128 v[130:133], v165 offset:8192
	s_mov_b64 s[12:13], 0
	s_waitcnt lgkmcnt(0)
	v_lshlrev_b32_e32 v138, 16, v130
	v_and_b32_e32 v139, 0xffff0000, v130
	v_lshlrev_b32_e32 v140, 16, v131
	v_and_b32_e32 v141, 0xffff0000, v131
	v_lshlrev_b32_e32 v130, 16, v132
	v_and_b32_e32 v131, 0xffff0000, v132
	v_lshlrev_b32_e32 v132, 16, v133
	v_and_b32_e32 v133, 0xffff0000, v133

.LBB0_830:
	v_mov_b64_e32 v[70:71], v[168:169]
	v_mov_b64_e32 v[72:73], v[170:171]
	v_mov_b64_e32 v[78:79], v[172:173]
	v_mov_b64_e32 v[80:81], v[174:175]
	s_and_b64 vcc, exec, s[10:11]
	s_mov_b64 s[12:13], -1
	s_cbranch_vccnz .LBB0_832
	ds_read_b128 v[62:65], v165 offset:16384
	s_mov_b64 s[12:13], 0
	s_waitcnt lgkmcnt(0)
	v_lshlrev_b32_e32 v74, 16, v62
	v_and_b32_e32 v75, 0xffff0000, v62
	v_lshlrev_b32_e32 v76, 16, v63
	v_and_b32_e32 v77, 0xffff0000, v63
	v_lshlrev_b32_e32 v62, 16, v64
	v_and_b32_e32 v63, 0xffff0000, v64
	v_lshlrev_b32_e32 v64, 16, v65
	v_and_b32_e32 v65, 0xffff0000, v65
.LBB0_832:
	s_andn2_b64 vcc, exec, s[12:13]
	s_cbranch_vccnz .LBB0_834
	global_load_dwordx4 v[62:65], v[152:153], off offset:528
	global_load_dwordx4 v[74:77], v[152:153], off offset:512
	s_waitcnt vmcnt(0)
.LBB0_834:
	v_mov_b32_e32 v156, v146
	v_mov_b32_e32 v157, v146
	v_pk_mul_f32 v[160:161], v[156:157], v[80:81]
	v_pk_mul_f32 v[154:155], v[146:147], v[78:79]
	v_pk_mul_f32 v[158:159], v[156:157], v[72:73]
	v_pk_mul_f32 v[156:157], v[146:147], v[70:71]
	v_pk_fma_f32 v[70:71], v[66:67], v[154:155], v[74:75]
	v_pk_fma_f32 v[72:73], v[68:69], v[160:161], v[76:77]
	v_pk_fma_f32 v[66:67], v[60:61], v[158:159], v[64:65]
	s_and_b64 vcc, exec, s[8:9]
	v_pk_fma_f32 v[68:69], v[58:59], v[156:157], v[62:63]
	s_cbranch_vccnz .LBB0_836
	v_cvt_pk_bf16_f32 v58, v70, v71
	v_cvt_pk_bf16_f32 v59, v72, v73
	v_cvt_pk_bf16_f32 v60, v68, v69
	v_cvt_pk_bf16_f32 v61, v66, v67
	global_store_dwordx4 v[150:151], v[58:61], off offset:256

.LBB0_903:
	s_or_b64 exec, exec, s[34:35]
	s_waitcnt lgkmcnt(0)
	s_barrier
	v_lshl_add_u64 v[158:159], v[148:149], 2, s[36:37]
	v_mov_b64_e32 v[2:3], v[176:177]
	v_mov_b64_e32 v[4:5], v[178:179]
	v_mov_b64_e32 v[6:7], v[180:181]
	v_mov_b64_e32 v[8:9], v[182:183]
	v_readlane_b32 s12, v255, 5
	v_readlane_b32 s13, v255, 4
	s_add_u32 s6, s72, s12
	s_addc_u32 s7, s73, 0
	s_lshl_b32 s10, s13, 2
	s_add_u32 s6, s6, s10
	s_addc_u32 s7, s7, 0
	s_add_u32 s4, s6, s4
	s_addc_u32 s5, s7, s5
	s_add_u32 s6, s4, 0x1000
	s_addc_u32 s7, s5, 0
	v_lshlrev_b64 v[12:13], 2, v[148:149]
	v_mov_b32_e32 v10, 0
	s_and_b64 vcc, exec, s[30:31]
	v_lshl_add_u64 v[160:161], s[6:7], 0, v[12:13]
	v_lshl_add_u64 v[150:151], s[4:5], 0, v[12:13]
	s_cbranch_vccz .LBB0_905
	v_mov_b64_e32 v[10:11], v[192:193]
	v_mov_b64_e32 v[12:13], v[194:195]
	v_mov_b64_e32 v[14:15], v[196:197]
	v_mov_b64_e32 v[16:17], v[198:199]
	v_pk_add_f32 v[12:13], v[12:13], 1.0 op_sel_hi:[1,0]
	v_pk_add_f32 v[16:17], v[16:17], 1.0 op_sel_hi:[1,0]
	v_pk_add_f32 v[14:15], v[14:15], 1.0 op_sel_hi:[1,0]
	v_pk_add_f32 v[10:11], v[10:11], 1.0 op_sel_hi:[1,0]
	v_pk_mul_f32 v[8:9], v[8:9], v[16:17]
	v_pk_mul_f32 v[6:7], v[6:7], v[14:15]
	v_pk_mul_f32 v[4:5], v[4:5], v[12:13]
	v_pk_mul_f32 v[2:3], v[2:3], v[10:11]
	v_mov_b64_e32 v[10:11], v[208:209]
	v_mov_b64_e32 v[12:13], v[210:211]
	v_mov_b64_e32 v[14:15], v[212:213]
	v_mov_b64_e32 v[16:17], v[214:215]
	s_branch .LBB0_906

.LBB0_906:
	v_lshl_add_u32 v0, v162, 2, 0
	ds_read_b32 v22, v0 offset:4096
	s_add_u32 s4, s18, 0x5400000
	s_addc_u32 s5, s19, 0
	s_mov_b64 s[10:11], -1
	s_and_b64 vcc, exec, s[30:31]
	s_waitcnt lgkmcnt(0)
	v_pk_mul_f32 v[18:19], v[134:135], v[22:23] op_sel_hi:[1,0]
	v_add_u32_e32 v134, s70, v162
	v_pk_mul_f32 v[20:21], v[136:137], v[22:23] op_sel_hi:[1,0]
	v_pk_mul_f32 v[130:131], v[130:131], v[22:23] op_sel_hi:[1,0]
	v_pk_mul_f32 v[22:23], v[132:133], v[22:23] op_sel_hi:[1,0]
	v_ashrrev_i32_e32 v135, 31, v134
	v_pk_fma_f32 v[24:25], v[4:5], v[22:23], v[16:17]
	v_pk_fma_f32 v[22:23], v[2:3], v[130:131], v[14:15]
	v_lshlrev_b64 v[130:131], 10, v[134:135]
	v_pk_fma_f32 v[20:21], v[8:9], v[20:21], v[12:13]
	v_pk_fma_f32 v[18:19], v[6:7], v[18:19], v[10:11]
	v_lshl_add_u64 v[132:133], v[130:131], 0, v[148:149]
	s_cbranch_vccz .LBB0_908
	v_lshl_add_u64 v[136:137], v[132:133], 1, s[4:5]
	v_cvt_pk_bf16_f32 v164, v18, v19
	v_cvt_pk_bf16_f32 v165, v20, v21
	v_cvt_pk_bf16_f32 v166, v22, v23
	v_cvt_pk_bf16_f32 v167, v24, v25
	global_store_dwordx4 v[136:137], v[164:167], off
	s_mov_b64 s[10:11], 0

.LBB0_938:
	s_nop 1
	v_mov_b64_e32 v[2:3], v[184:185]
	v_mov_b64_e32 v[4:5], v[186:187]
	v_mov_b64_e32 v[6:7], v[188:189]
	v_mov_b64_e32 v[8:9], v[190:191]
	s_and_b64 vcc, exec, s[8:9]
	v_mov_b32_e32 v10, 0
	s_cbranch_vccnz .LBB0_940
	v_mov_b64_e32 v[10:11], v[200:201]
	v_mov_b64_e32 v[12:13], v[202:203]
	v_mov_b64_e32 v[14:15], v[204:205]
	v_mov_b64_e32 v[16:17], v[206:207]
	v_pk_add_f32 v[12:13], v[12:13], 1.0 op_sel_hi:[1,0]
	v_pk_add_f32 v[16:17], v[16:17], 1.0 op_sel_hi:[1,0]
	v_pk_add_f32 v[14:15], v[14:15], 1.0 op_sel_hi:[1,0]
	v_pk_add_f32 v[10:11], v[10:11], 1.0 op_sel_hi:[1,0]
	v_pk_mul_f32 v[8:9], v[8:9], v[16:17]
	v_pk_mul_f32 v[6:7], v[6:7], v[14:15]
	v_pk_mul_f32 v[4:5], v[4:5], v[12:13]
	v_pk_mul_f32 v[2:3], v[2:3], v[10:11]
	v_mov_b64_e32 v[10:11], v[220:221]
	v_mov_b64_e32 v[12:13], v[222:223]
	v_mov_b64_e32 v[14:15], v[224:225]
	v_mov_b64_e32 v[16:17], v[226:227]
	s_branch .LBB0_941

.LBB0_941:
	ds_read_b32 v22, v0 offset:4096
	v_or_b32_e32 v94, 0x80, v148
	v_ashrrev_i32_e32 v95, 31, v94
	s_and_b64 vcc, exec, s[8:9]
	s_mov_b64 s[10:11], -1
	s_waitcnt lgkmcnt(0)
	v_pk_mul_f32 v[18:19], v[72:73], v[22:23] op_sel_hi:[1,0]
	v_pk_mul_f32 v[24:25], v[70:71], v[22:23] op_sel_hi:[1,0]
	v_pk_fma_f32 v[20:21], v[8:9], v[18:19], v[12:13]
	v_pk_fma_f32 v[18:19], v[6:7], v[24:25], v[10:11]
	v_pk_mul_f32 v[24:25], v[66:67], v[22:23] op_sel_hi:[1,0]
	v_pk_mul_f32 v[22:23], v[68:69], v[22:23] op_sel_hi:[1,0]
	v_pk_fma_f32 v[24:25], v[4:5], v[24:25], v[16:17]
	v_pk_fma_f32 v[22:23], v[2:3], v[22:23], v[14:15]
	s_cbranch_vccnz .LBB0_943
	v_lshl_add_u64 v[70:71], v[130:131], 0, v[94:95]
	v_lshl_add_u64 v[70:71], v[70:71], 1, s[4:5]
	s_mov_b64 s[10:11], 0
	v_cvt_pk_bf16_f32 v66, v18, v19
	v_cvt_pk_bf16_f32 v67, v20, v21
	v_cvt_pk_bf16_f32 v68, v22, v23
	v_cvt_pk_bf16_f32 v69, v24, v25
	global_store_dwordx4 v[70:71], v[66:69], off

	.amdhsa_kernel _ZN12_GLOBAL__N_12mkENS_6ParamsE
		.amdhsa_group_segment_fixed_size 0
		.amdhsa_private_segment_fixed_size 0
		.amdhsa_kernarg_size 488
		.amdhsa_user_sgpr_count 2
		.amdhsa_user_sgpr_dispatch_ptr 0
		.amdhsa_user_sgpr_queue_ptr 0
		.amdhsa_user_sgpr_kernarg_segment_ptr 1
		.amdhsa_user_sgpr_dispatch_id 0
		.amdhsa_user_sgpr_kernarg_preload_length 0
		.amdhsa_user_sgpr_kernarg_preload_offset 0
		.amdhsa_user_sgpr_private_segment_size 0
		.amdhsa_uses_dynamic_stack 0
		.amdhsa_enable_private_segment 0
		.amdhsa_system_sgpr_workgroup_id_x 1
		.amdhsa_system_sgpr_workgroup_id_y 0
		.amdhsa_system_sgpr_workgroup_id_z 0
		.amdhsa_system_sgpr_workgroup_info 0
		.amdhsa_system_vgpr_workitem_id 2
		.amdhsa_next_free_vgpr 256
		.amdhsa_next_free_sgpr 102
		.amdhsa_accum_offset 256
		.amdhsa_reserve_vcc 1
		.amdhsa_float_round_mode_32 0
		.amdhsa_float_round_mode_16_64 0
		.amdhsa_float_denorm_mode_32 3
		.amdhsa_float_denorm_mode_16_64 3
		.amdhsa_dx10_clamp 1
		.amdhsa_ieee_mode 1
		.amdhsa_fp16_overflow 0
		.amdhsa_tg_split 0
		.amdhsa_exception_fp_ieee_invalid_op 0
		.amdhsa_exception_fp_denorm_src 0
		.amdhsa_exception_fp_ieee_div_zero 0
		.amdhsa_exception_fp_ieee_overflow 0
		.amdhsa_exception_fp_ieee_underflow 0
		.amdhsa_exception_fp_ieee_inexact 0
		.amdhsa_exception_int_div_zero 0
	.end_amdhsa_kernel

amdhsa.kernels:
  - .agpr_count:     0
    .args:
      - .offset:         0
        .size:           232
        .value_kind:     by_value
      - .offset:         232
        .size:           4
        .value_kind:     hidden_block_count_x
      - .offset:         236
        .size:           4
        .value_kind:     hidden_block_count_y
      - .offset:         240
        .size:           4
        .value_kind:     hidden_block_count_z
      - .offset:         244
        .size:           2
        .value_kind:     hidden_group_size_x
      - .offset:         246
        .size:           2
        .value_kind:     hidden_group_size_y
      - .offset:         248
        .size:           2
        .value_kind:     hidden_group_size_z
      - .offset:         250
        .size:           2
        .value_kind:     hidden_remainder_x
      - .offset:         252
        .size:           2
        .value_kind:     hidden_remainder_y
      - .offset:         254
        .size:           2
        .value_kind:     hidden_remainder_z
      - .offset:         272
        .size:           8
        .value_kind:     hidden_global_offset_x
      - .offset:         280
        .size:           8
        .value_kind:     hidden_global_offset_y
      - .offset:         288
        .size:           8
        .value_kind:     hidden_global_offset_z
      - .offset:         296
        .size:           2
        .value_kind:     hidden_grid_dims
      - .offset:         320
        .size:           8
        .value_kind:     hidden_multigrid_sync_arg
      - .offset:         352
        .size:           4
        .value_kind:     hidden_dynamic_lds_size
    .group_segment_fixed_size: 0
    .kernarg_segment_align: 8
    .kernarg_segment_size: 488
    .language:       OpenCL C
    .language_version:
      - 2
      - 0
    .max_flat_workgroup_size: 512
    .name:           _ZN12_GLOBAL__N_12mkENS_6ParamsE
    .private_segment_fixed_size: 0
    .sgpr_count:     108
    .sgpr_spill_count: 112
    .symbol:         _ZN12_GLOBAL__N_12mkENS_6ParamsE.kd
    .uniform_work_group_size: 1
    .uses_dynamic_stack: false
    .vgpr_count:     256
    .vgpr_spill_count: 0
    .wavefront_size: 64
